# GDN chain waves at priority 1 (MLA-side waves stay at 0)
# baseline (speedup 1.0000x reference)
; DI void gdn_chain(const P& p, int cid, char* smem) {
;   const int eb = cid & 1, chn = cid >> 1;
;   const int dir = chn >> 6, b = (chn >> 3) & 7, h = chn & 7;
;   float* qs = (float*)smem;
;   float* ks = qs + 4096;
;   float* vs = ks + 4096;
;   float* ob = vs + 2048;
;   float* ps = ob + 2048;
;   float* cw = ps + 256;
;   const int tid = get_tid(), lane = tid & 63, wave = tid >> 6;
;   const u16* z = (const u16*)(p.ws + OFF_REGB);
;   const float* side = (const float*)(p.ws + OFF_SIDE);
;   u16* od = (u16*)(p.ws + OFF_ODIR) + (size_t)dir * T * 512;
;   __syncthreads();
;   for (int i = tid; i < 800; i += NTHR) {
;     const int j = i / 160, cc = i % 160;
;     const int chi = cc < 64 ? h * 64 + cc : (cc < 128 ? 512 + h * 64 + (cc - 64) : 1024 + h * 64 + eb * 32 + (cc - 128));
;     cw[i] = p.ev_conv[j * 1536 + chi];
;   }
;   const float Aexp = __expf(p.ev_a_log[dir * 8 + h]);
;   const float dtb = p.ev_dt_bias[dir * 8 + h];
;   __builtin_amdgcn_s_setprio(3);
;   f32x2 S[4];
; #pragma unroll
;   for (int i = 0; i < 4; ++i) S[i] = (f32x2){0.f, 0.f};
;   const int dl = lane & 7, ec = wave * 8 + (lane >> 3);
;   const int pp = tid >> 2, qd = tid & 3;
;   __syncthreads();
.LBB0_946:
	s_or_b64 exec, exec, s[4:5]
	s_ashr_i32 s0, s44, 7
	s_bfe_u32 s1, s44, 0x30004
	s_mul_i32 s5, s0, 0x1200000
	s_mul_hi_i32 s4, s0, 0x1200000
	s_add_u32 s17, s92, s5
	s_addc_u32 s20, s93, s4
	s_lshl_b32 s0, s0, 3
	s_or_b32 s4, s0, s15
	s_ashr_i32 s5, s4, 31
	v_readlane_b32 s72, v223, 38
	s_lshl_b64 s[4:5], s[4:5], 2
	v_readlane_b32 s76, v223, 42
	v_readlane_b32 s77, v223, 43
	s_add_u32 s18, s76, s4
	v_readlane_b32 s78, v223, 44
	s_addc_u32 s19, s77, s5
	v_readlane_b32 s79, v223, 45
	s_add_u32 s4, s78, s4
	global_load_dword v1, v96, s[18:19]
	s_addc_u32 s5, s79, s5
	global_load_dword v49, v96, s[4:5]
	v_readlane_b32 s74, v223, 40
	v_readlane_b32 s75, v223, 41
	v_readlane_b32 s80, v223, 46
	v_readlane_b32 s81, v223, 47
	v_readlane_b32 s82, v223, 48
	v_readlane_b32 s83, v223, 49
	v_readlane_b32 s84, v223, 50
	v_readlane_b32 s85, v223, 51
	v_readlane_b32 s86, v223, 52
	v_readlane_b32 s87, v223, 53
	v_readlane_b32 s73, v223, 39
	s_waitcnt vmcnt(1)
	v_mul_f32_e32 v1, 0x3fb8aa3b, v1
	s_setprio 1
	s_lshl_b32 s46, s1, 8
	s_bitset1_b32 s46, 14
	s_lshl_b32 s47, s1, 11
	s_cmpk_lt_u32 s44, 0x80
	s_cselect_b64 s[74:75], -1, 0
	s_lshl_b32 s1, s16, 1
	v_readlane_b32 s4, v221, 5
	v_readlane_b32 s5, v221, 6
	s_add_u32 s38, s4, s1
	s_addc_u32 s39, s5, 0
	s_add_u32 s1, s17, s1
	s_addc_u32 s5, s20, 0
	s_lshl_b32 s4, s45, 1
	v_ashrrev_i32_e32 v69, 2, v0
	v_and_b32_e32 v3, 3, v0
	s_add_u32 s4, s1, s4
	v_exp_f32_e32 v51, v1
	v_ashrrev_i32_e32 v1, 3, v0
	v_lshrrev_b32_e32 v2, 3, v0
	v_lshlrev_b32_e32 v5, 6, v3
	v_lshl_add_u32 v6, v69, 8, 0
	s_addc_u32 s5, s5, 0
	s_ashr_i32 s1, s0, 31
	v_bfi_b32 v2, -8, v1, v2
	v_add_u32_e32 v70, 0, v5
	v_add_u32_e32 v71, v6, v5
	v_lshlrev_b32_e32 v5, 7, v69
	s_lshl_b64 s[0:1], s[0:1], 2
	v_lshlrev_b32_e32 v48, 4, v3
	v_lshlrev_b32_e32 v50, 3, v3
	v_sub_u32_e32 v5, v6, v5
	v_lshlrev_b32_e32 v6, 5, v3
	v_cmp_eq_u32_e64 s[76:77], 0, v3
	v_ashrrev_i32_e32 v3, 31, v2
	s_add_u32 s0, s36, s0
	v_bfe_u32 v4, v0, 3, 3
	v_lshl_add_u32 v8, v2, 2, 0
	v_lshl_add_u64 v[52:53], v[2:3], 1, s[4:5]
	v_and_b32_e32 v2, 0x3ffffff8, v0
	s_addc_u32 s1, s37, s1
	s_lshl_b32 s4, s15, 2
	v_and_b32_e32 v68, 7, v0
	v_lshl_add_u32 v73, v2, 2, 0
	v_and_b32_e32 v2, 4, v0
	s_add_u32 s40, s0, s4
	v_bitop3_b32 v75, v0, 7, v0 bitop3:0x3f
	v_lshlrev_b32_e32 v0, 2, v1
	v_lshlrev_b32_e32 v1, 2, v4
	s_movk_i32 s0, 0xffe0
	v_and_or_b32 v0, v0, s0, v1
	v_readlane_b32 s0, v218, 42
	v_lshlrev_b32_e32 v7, 5, v68
	v_cmp_ne_u32_e64 s[94:95], 0, v2
	v_sub_u32_e32 v2, 0, v6
	s_addc_u32 s41, s1, 0
	v_add_u32_e32 v76, s0, v0
	s_add_i32 s0, 0, 0x200
	v_mov_b32_e32 v97, v96
	v_add_u32_e32 v72, 0, v7
	v_sub_u32_e32 v74, v70, v6
	v_add_u32_e32 v77, s0, v7
	v_mov_b32_e32 v98, v96
	v_mov_b32_e32 v99, v96
	v_mov_b32_e32 v100, v96
	v_mov_b32_e32 v101, v96
	v_mov_b32_e32 v102, v96
	v_mov_b32_e32 v103, v96
	v_add_u32_e32 v78, v70, v2
	v_add_u32_e32 v79, v5, v6
	v_mov_b64_e32 v[0:1], v[96:97]
	v_cmp_eq_u32_e64 s[78:79], 0, v68
	v_cmp_eq_u32_e64 s[80:81], 1, v68
	v_cmp_eq_u32_e64 s[82:83], 2, v68
	v_cmp_eq_u32_e64 s[84:85], 3, v68
	v_cmp_eq_u32_e64 s[86:87], 4, v68
	v_cmp_eq_u32_e64 s[88:89], 5, v68
	v_cmp_eq_u32_e64 s[90:91], 6, v68
	v_cmp_eq_u32_e64 s[92:93], 7, v68
	s_mov_b64 s[0:1], -1
	v_add_u32_e32 v80, 0x8000, v8
	v_mov_b64_e32 v[2:3], v[98:99]
	v_mov_b64_e32 v[4:5], v[100:101]
	v_mov_b64_e32 v[6:7], v[102:103]
	s_waitcnt lgkmcnt(0)
	s_barrier
